# baseline (speedup 1.0000x reference)
; #define SBAR() __builtin_amdgcn_sched_barrier(0)
; #define MASK(P0, P1, t) do { if (BANDED) band_mask(P0, P1, rel00 + (t) * KVBLK, mlo, mhi); } while (0)
; __device__ __forceinline__ void finishSM(f32x16& p0, f32x16& p1, float alpha, float& l_reg, bf16x8& pa0, bf16x8& pa1, bf16x8& pa2, bf16x8& pa3) {
; #pragma unroll
;   for (int r = 0; r < 16; ++r) p1[r] = __builtin_amdgcn_exp2f(p1[r]);
;   float ps = 0;
; #pragma unroll
;   for (int r = 0; r < 16; ++r) ps += p0[r];
; #pragma unroll
;   for (int r = 0; r < 16; ++r) ps += p1[r];
;   { auto rr = __builtin_amdgcn_permlane32_swap(__float_as_uint(ps), __float_as_uint(ps), false, false);
;     ps = __uint_as_float(rr[0]) + __uint_as_float(rr[1]); }
;   l_reg = l_reg * alpha + ps;
;     ...
;   PK4(p0, 0, pa0); PK4(p0, 8, pa1); PK4(p1, 0, pa2); PK4(p1, 8, pa3);
;     ...
; }
; template <bool BANDED, bool FIXED> ...
;     ...
;     SBAR(); if (FIXED) qkt_c(pB0, pB1, (bf16*)((char*)K_lds + SHM_K), qr, r32, hi); else qkt(pB0, pB1, (bf16*)((char*)K_lds + SHM_K), qr, r32, hi, 0.f); MASK(pB0, pB1, j);
;     finishSM(pA0, pA1, alA, l_reg, pa0, pa1, pa2, pa3); SBAR();
;     SLOAD(SO, j + 2); SBAR();
;     pv_d0(o, vb0, pa0, pa1, pa2, pa3); partialSM<FIXED, !BANDED>(pB0, pB1, m_reg, mnB, alB);
.LBB0_118:
	s_add_i32 s2, s2, 2
	ds_read_b128 v[10:13], v201 offset:49152
	ds_read_b128 v[176:179], v201 offset:57344
	ds_read_b128 v[188:191], v202 offset:49152
	ds_read_b128 v[192:195], v202 offset:57344
	v_exp_f32_e32 v88, v88
	v_exp_f32_e32 v89, v89
	v_exp_f32_e32 v90, v90
	v_exp_f32_e32 v91, v91
	v_exp_f32_e32 v92, v92
	v_exp_f32_e32 v93, v93
	v_exp_f32_e32 v94, v94
	v_exp_f32_e32 v95, v95
	s_waitcnt lgkmcnt(5)
	v_mfma_f32_32x32x16_bf16 v[112:127], v[2:5], v[156:159], 0
	s_waitcnt lgkmcnt(4)
	v_mfma_f32_32x32x16_bf16 v[96:111], v[6:9], v[156:159], 0
	ds_read_b128 v[2:5], v203 offset:49152
	ds_read_b128 v[6:9], v203 offset:57344
	s_waitcnt lgkmcnt(5)
	v_mfma_f32_32x32x16_bf16 v[112:127], v[10:13], v[152:155], v[112:127]
	s_waitcnt lgkmcnt(4)
	v_mfma_f32_32x32x16_bf16 v[96:111], v[176:179], v[152:155], v[96:111]
	ds_read_b128 v[10:13], v206 offset:49152
	ds_read_b128 v[176:179], v206 offset:57344
	s_waitcnt lgkmcnt(5)
	v_mfma_f32_32x32x16_bf16 v[112:127], v[188:191], v[148:151], v[112:127]
	s_waitcnt lgkmcnt(4)
	v_mfma_f32_32x32x16_bf16 v[96:111], v[192:195], v[148:151], v[96:111]
	ds_read_b128 v[188:191], v204 offset:49152
	ds_read_b128 v[192:195], v204 offset:57344
	s_waitcnt lgkmcnt(5)
	v_mfma_f32_32x32x16_bf16 v[112:127], v[2:5], v[144:147], v[112:127]
	s_waitcnt lgkmcnt(4)
	v_mfma_f32_32x32x16_bf16 v[96:111], v[6:9], v[144:147], v[96:111]
	ds_read_b128 v[2:5], v205 offset:49152
	ds_read_b128 v[6:9], v205 offset:57344
	v_add_u32_e32 v254, vcc_lo, v184
	v_add_u32_e32 v255, vcc_lo, v185
	s_waitcnt vmcnt(0)
	ds_write_b128 v254, v[160:163]
	s_waitcnt lgkmcnt(6)
	v_mfma_f32_32x32x16_bf16 v[112:127], v[10:13], v[140:143], v[112:127]
	s_waitcnt lgkmcnt(5)
	v_mfma_f32_32x32x16_bf16 v[96:111], v[176:179], v[140:143], v[96:111]
	ds_read_b128 v[10:13], v207 offset:49152
	ds_read_b128 v[176:179], v207 offset:57344
	ds_write_b128 v255, v[164:167]
	s_waitcnt lgkmcnt(7)
	v_mfma_f32_32x32x16_bf16 v[112:127], v[188:191], v[136:139], v[112:127]
	s_waitcnt lgkmcnt(6)
	v_mfma_f32_32x32x16_bf16 v[96:111], v[192:195], v[136:139], v[96:111]
	ds_write_b128 v198, v[168:171] offset:32768
	s_waitcnt lgkmcnt(6)
	v_mfma_f32_32x32x16_bf16 v[112:127], v[2:5], v[132:135], v[112:127]
	s_waitcnt lgkmcnt(5)
	v_mfma_f32_32x32x16_bf16 v[96:111], v[6:9], v[132:135], v[96:111]
	ds_write_b128 v199, v[172:175] offset:32768
	s_waitcnt lgkmcnt(4)
	v_mfma_f32_32x32x16_bf16 v[112:127], v[10:13], v[128:131], v[112:127]
	s_waitcnt lgkmcnt(3)
	v_mfma_f32_32x32x16_bf16 v[96:111], v[176:179], v[128:131], v[96:111]
	s_add_i32 s100, s2, 2
	s_mul_i32 s100, s100, 0x60000
	v_add_u32_e32 v254, s100, v14
	v_add_u32_e32 v255, s100, v15
	global_load_dwordx4 v[2:5], v254, s[58:59]
	global_load_dwordx4 v[6:9], v255, s[58:59]
	global_load_dwordx4 v[10:13], v254, s[8:9]
	global_load_dwordx4 v[176:179], v255, s[8:9]
	v_exp_f32_e32 v188, v80
	v_add_f32_e32 v80, 0, v223
	v_add_f32_e32 v80, v225, v80
	v_add_f32_e32 v80, v221, v80
	v_add_f32_e32 v80, v224, v80
	v_add_f32_e32 v80, v220, v80
	v_add_f32_e32 v80, v222, v80
	v_add_f32_e32 v80, v218, v80
	v_add_f32_e32 v80, v219, v80
	v_add_f32_e32 v80, v215, v80
	v_add_f32_e32 v80, v217, v80
	v_add_f32_e32 v80, v214, v80
	v_add_f32_e32 v80, v216, v80
	v_add_f32_e32 v80, v210, v80
	v_exp_f32_e32 v189, v81
	v_add_f32_e32 v80, v213, v80
	v_exp_f32_e32 v190, v82
	v_add_f32_e32 v80, v211, v80
	v_exp_f32_e32 v191, v83
	v_add_f32_e32 v80, v212, v80
	v_exp_f32_e32 v192, v84
	v_add_f32_e32 v80, v188, v80
	v_exp_f32_e32 v193, v85
	v_add_f32_e32 v80, v189, v80
	v_exp_f32_e32 v194, v86
	v_add_f32_e32 v80, v190, v80
	v_exp_f32_e32 v195, v87
	v_add_f32_e32 v80, v191, v80
	v_add_f32_e32 v80, v192, v80
	v_add_f32_e32 v80, v193, v80
	v_add_f32_e32 v80, v194, v80
	v_add_f32_e32 v80, v195, v80
	v_add_f32_e32 v80, v88, v80
	v_add_f32_e32 v80, v89, v80
	v_add_f32_e32 v80, v90, v80
	v_add_f32_e32 v80, v91, v80
	v_add_f32_e32 v80, v92, v80
	v_add_f32_e32 v80, v93, v80
	v_add_f32_e32 v80, v94, v80
	v_add_f32_e32 v80, v95, v80
	v_mov_b32_e32 v81, v80
	s_nop 1
	v_permlane32_swap_b32_e32 v80, v81
	v_add_f32_e32 v80, v80, v81
	v_add_f32_e32 v226, v183, v80
	v_cvt_pk_bf16_f32 v80, v223, v225
	v_cvt_pk_bf16_f32 v81, v221, v224
	v_cvt_pk_bf16_f32 v82, v220, v222
	v_cvt_pk_bf16_f32 v83, v218, v219
	v_cvt_pk_bf16_f32 v84, v215, v217
	v_cvt_pk_bf16_f32 v85, v214, v216
	v_cvt_pk_bf16_f32 v86, v210, v213
	v_cvt_pk_bf16_f32 v87, v211, v212
	v_cvt_pk_bf16_f32 v95, v94, v95
	v_cvt_pk_bf16_f32 v94, v92, v93
	v_cvt_pk_bf16_f32 v93, v90, v91
	v_cvt_pk_bf16_f32 v92, v88, v89
	v_cvt_pk_bf16_f32 v88, v188, v189
	v_cvt_pk_bf16_f32 v89, v190, v191
	v_cvt_pk_bf16_f32 v90, v192, v193
	v_cvt_pk_bf16_f32 v91, v194, v195
	v_permlane32_swap_b32_e32 v80, v82
	v_permlane32_swap_b32_e32 v81, v83
	v_permlane32_swap_b32_e32 v84, v86
	v_permlane32_swap_b32_e32 v85, v87
	v_permlane32_swap_b32_e32 v88, v90
	v_permlane32_swap_b32_e32 v89, v91
	v_permlane32_swap_b32_e32 v93, v95
	v_permlane32_swap_b32_e32 v92, v94
	v_add_u32_e32 v255, vcc_hi, v208
	ds_read_b64_tr_b16 v[210:211], v255 offset:0
	ds_read_b64_tr_b16 v[212:213], v255 offset:0x800
	ds_read_b64_tr_b16 v[214:215], v255 offset:0x1000
	ds_read_b64_tr_b16 v[216:217], v255 offset:0x1800
	ds_read_b64_tr_b16 v[218:219], v255 offset:0x2000
	ds_read_b64_tr_b16 v[220:221], v255 offset:0x2800
	ds_read_b64_tr_b16 v[222:223], v255 offset:0x3000
	ds_read_b64_tr_b16 v[224:225], v255 offset:0x3800
	s_waitcnt lgkmcnt(0)
; #define SBAR() __builtin_amdgcn_sched_barrier(0)
; #define SWAIT() asm volatile("s_waitcnt vmcnt(4)" ::: "memory")
; #define RESC(a) do { if (!FIXED && __any((a) < 1.f)) { if (hi == 0) al_l[r32] = (a); asm volatile("s_waitcnt lgkmcnt(0)" ::: "memory"); \
;     _Pragma("unroll") for (int d = 0; d < 4; ++d) _Pragma("unroll") for (int r = 0; r < 16; ++r) o[d][r] *= al_l[crow(r, hi)]; } } while (0)
; #define MASK(P0, P1, t) do { if (BANDED) band_mask(P0, P1, rel00 + (t) * KVBLK, mlo, mhi); } while (0)
; template <bool BANDED, bool FIXED> ...
;     ...
;     __syncthreads(); SWAIT(); SWRITE(0, SE);
;     RESC(alB); __syncthreads();
;     SBAR(); if (FIXED) qkt_c(pA0, pA1, K_lds, qr, r32, hi); else qkt(pA0, pA1, K_lds, qr, r32, hi, 0.f); MASK(pA0, pA1, j + 1);
;     finishSM(pB0, pB1, alB, l_reg, pa0, pa1, pa2, pa3); SBAR();
;     SLOAD(SE, min(j + 3, NT - 1)); SBAR();
;     pv_d0(o, vb0 + (int)SHM_V, pa0, pa1, pa2, pa3); partialSM<FIXED, !BANDED>(pA0, pA1, m_reg, mnA, alA);
	s_nop 0
	v_mfma_f32_32x32x16_bf16 v[16:31], v[80:83], v[210:213], v[16:31]
	ds_read_b64_tr_b16 v[210:211], v255 offset:0x200
	ds_read_b64_tr_b16 v[212:213], v255 offset:0xa00
	v_mfma_f32_32x32x16_bf16 v[16:31], v[84:87], v[214:217], v[16:31]
	ds_read_b64_tr_b16 v[214:215], v255 offset:0x1200
	ds_read_b64_tr_b16 v[216:217], v255 offset:0x1a00
	v_mfma_f32_32x32x16_bf16 v[16:31], v[88:91], v[218:221], v[16:31]
	ds_read_b64_tr_b16 v[218:219], v255 offset:0x2200
	ds_read_b64_tr_b16 v[220:221], v255 offset:0x2a00
	v_mfma_f32_32x32x16_bf16 v[16:31], v[92:95], v[222:225], v[16:31]
	ds_read_b64_tr_b16 v[222:223], v255 offset:0x3200
	ds_read_b64_tr_b16 v[224:225], v255 offset:0x3a00
	s_waitcnt lgkmcnt(0)
	v_mfma_f32_32x32x16_bf16 v[32:47], v[80:83], v[210:213], v[32:47]
	ds_read_b64_tr_b16 v[210:211], v255 offset:0x400
	ds_read_b64_tr_b16 v[212:213], v255 offset:0xc00
	v_mfma_f32_32x32x16_bf16 v[32:47], v[84:87], v[214:217], v[32:47]
	ds_read_b64_tr_b16 v[214:215], v255 offset:0x1400
	ds_read_b64_tr_b16 v[216:217], v255 offset:0x1c00
	v_mfma_f32_32x32x16_bf16 v[32:47], v[88:91], v[218:221], v[32:47]
	ds_read_b64_tr_b16 v[218:219], v255 offset:0x2400
	ds_read_b64_tr_b16 v[220:221], v255 offset:0x2c00
	v_mfma_f32_32x32x16_bf16 v[32:47], v[92:95], v[222:225], v[32:47]
	ds_read_b64_tr_b16 v[222:223], v255 offset:0x3400
	ds_read_b64_tr_b16 v[224:225], v255 offset:0x3c00
	s_waitcnt lgkmcnt(0)
	v_mfma_f32_32x32x16_bf16 v[48:63], v[80:83], v[210:213], v[48:63]
	ds_read_b64_tr_b16 v[210:211], v255 offset:0x600
	ds_read_b64_tr_b16 v[212:213], v255 offset:0xe00
	v_mfma_f32_32x32x16_bf16 v[48:63], v[84:87], v[214:217], v[48:63]
	ds_read_b64_tr_b16 v[214:215], v255 offset:0x1600
	ds_read_b64_tr_b16 v[216:217], v255 offset:0x1e00
	v_mfma_f32_32x32x16_bf16 v[48:63], v[88:91], v[218:221], v[48:63]
	ds_read_b64_tr_b16 v[218:219], v255 offset:0x2600
	ds_read_b64_tr_b16 v[220:221], v255 offset:0x2e00
	v_mfma_f32_32x32x16_bf16 v[48:63], v[92:95], v[222:225], v[48:63]
	ds_read_b64_tr_b16 v[222:223], v255 offset:0x3600
	ds_read_b64_tr_b16 v[224:225], v255 offset:0x3e00
	s_waitcnt lgkmcnt(0)
	v_mfma_f32_32x32x16_bf16 v[64:79], v[80:83], v[210:213], v[64:79]
	v_exp_f32_e32 v210, v112
	v_exp_f32_e32 v211, v113
	v_exp_f32_e32 v212, v114
	v_exp_f32_e32 v213, v115
	v_mfma_f32_32x32x16_bf16 v[64:79], v[84:87], v[214:217], v[64:79]
	v_exp_f32_e32 v214, v116
	v_exp_f32_e32 v215, v117
	v_exp_f32_e32 v216, v118
	v_exp_f32_e32 v217, v119
	v_mfma_f32_32x32x16_bf16 v[64:79], v[88:91], v[218:221], v[64:79]
	v_exp_f32_e32 v218, v120
	v_exp_f32_e32 v219, v121
	v_exp_f32_e32 v220, v122
	v_exp_f32_e32 v221, v123
	s_mov_b32 s100, vcc_lo
	s_mov_b32 vcc_lo, vcc_hi
	s_mov_b32 vcc_hi, s101
	s_mov_b32 s101, s100
	s_waitcnt lgkmcnt(0)
	s_barrier
	ds_read_b128 v[80:83], v200 offset:32768
	ds_read_b128 v[84:87], v200 offset:40960
	v_mfma_f32_32x32x16_bf16 v[64:79], v[92:95], v[222:225], v[64:79]
	ds_read_b128 v[160:163], v201 offset:32768
	ds_read_b128 v[164:167], v201 offset:40960
	ds_read_b128 v[168:171], v202 offset:32768
	ds_read_b128 v[172:175], v202 offset:40960
	ds_read_b128 v[188:191], v203 offset:32768
	ds_read_b128 v[192:195], v203 offset:40960
	v_exp_f32_e32 v222, v124
	v_exp_f32_e32 v223, v125
	v_exp_f32_e32 v224, v126
	v_exp_f32_e32 v225, v127
	v_exp_f32_e32 v104, v104
	v_exp_f32_e32 v105, v105
	v_exp_f32_e32 v106, v106
	v_exp_f32_e32 v107, v107
	v_exp_f32_e32 v108, v108
	v_exp_f32_e32 v109, v109
	v_exp_f32_e32 v110, v110
	v_exp_f32_e32 v111, v111
	s_waitcnt lgkmcnt(7)
	v_mfma_f32_32x32x16_bf16 v[112:127], v[80:83], v[156:159], 0
	s_waitcnt lgkmcnt(6)
	v_mfma_f32_32x32x16_bf16 v[80:95], v[84:87], v[156:159], 0
	s_waitcnt lgkmcnt(5)
	v_mfma_f32_32x32x16_bf16 v[112:127], v[160:163], v[152:155], v[112:127]
	s_waitcnt lgkmcnt(4)
	v_mfma_f32_32x32x16_bf16 v[80:95], v[164:167], v[152:155], v[80:95]
	ds_read_b128 v[160:163], v206 offset:32768
	ds_read_b128 v[164:167], v206 offset:40960
	s_waitcnt lgkmcnt(5)
	v_mfma_f32_32x32x16_bf16 v[112:127], v[168:171], v[148:151], v[112:127]
	s_waitcnt lgkmcnt(4)
	v_mfma_f32_32x32x16_bf16 v[80:95], v[172:175], v[148:151], v[80:95]
	ds_read_b128 v[168:171], v204 offset:32768
	ds_read_b128 v[172:175], v204 offset:40960
	s_waitcnt lgkmcnt(5)
	v_mfma_f32_32x32x16_bf16 v[112:127], v[188:191], v[144:147], v[112:127]
	s_waitcnt lgkmcnt(4)
	v_mfma_f32_32x32x16_bf16 v[80:95], v[192:195], v[144:147], v[80:95]
	ds_read_b128 v[188:191], v205 offset:32768
	ds_read_b128 v[192:195], v205 offset:40960
	v_add_u32_e32 v254, vcc_lo, v184
	v_add_u32_e32 v255, vcc_lo, v185
	s_waitcnt vmcnt(0)
	ds_write_b128 v254, v[2:5]
	s_waitcnt lgkmcnt(6)
	v_mfma_f32_32x32x16_bf16 v[112:127], v[160:163], v[140:143], v[112:127]
	s_waitcnt lgkmcnt(5)
	v_mfma_f32_32x32x16_bf16 v[80:95], v[164:167], v[140:143], v[80:95]
	ds_read_b128 v[160:163], v207 offset:32768
	ds_read_b128 v[164:167], v207 offset:40960
	ds_write_b128 v255, v[6:9]
	s_waitcnt lgkmcnt(7)
	v_mfma_f32_32x32x16_bf16 v[112:127], v[168:171], v[136:139], v[112:127]
	s_waitcnt lgkmcnt(6)
	v_mfma_f32_32x32x16_bf16 v[80:95], v[172:175], v[136:139], v[80:95]
	ds_write_b128 v198, v[10:13] offset:49152
	s_waitcnt lgkmcnt(6)
	v_mfma_f32_32x32x16_bf16 v[112:127], v[188:191], v[132:135], v[112:127]
	s_waitcnt lgkmcnt(5)
	v_mfma_f32_32x32x16_bf16 v[80:95], v[192:195], v[132:135], v[80:95]
	ds_write_b128 v199, v[176:179] offset:49152
	s_waitcnt lgkmcnt(4)
	v_mfma_f32_32x32x16_bf16 v[112:127], v[160:163], v[128:131], v[112:127]
	s_waitcnt lgkmcnt(3)
; #define SBAR() __builtin_amdgcn_sched_barrier(0)
; #define SWAIT() asm volatile("s_waitcnt vmcnt(4)" ::: "memory")
; #define RESC(a) do { if (!FIXED && __any((a) < 1.f)) { if (hi == 0) al_l[r32] = (a); asm volatile("s_waitcnt lgkmcnt(0)" ::: "memory"); \
;     _Pragma("unroll") for (int d = 0; d < 4; ++d) _Pragma("unroll") for (int r = 0; r < 16; ++r) o[d][r] *= al_l[crow(r, hi)]; } } while (0)
; #define MASK(P0, P1, t) do { if (BANDED) band_mask(P0, P1, rel00 + (t) * KVBLK, mlo, mhi); } while (0)
; __device__ __forceinline__ void finishSM(f32x16& p0, f32x16& p1, float alpha, float& l_reg, bf16x8& pa0, bf16x8& pa1, bf16x8& pa2, bf16x8& pa3) {
; #pragma unroll
;   for (int r = 0; r < 16; ++r) p1[r] = __builtin_amdgcn_exp2f(p1[r]);
;   float ps = 0;
; #pragma unroll
;   for (int r = 0; r < 16; ++r) ps += p0[r];
; #pragma unroll
;   for (int r = 0; r < 16; ++r) ps += p1[r];
;   { auto rr = __builtin_amdgcn_permlane32_swap(__float_as_uint(ps), __float_as_uint(ps), false, false);
;     ps = __uint_as_float(rr[0]) + __uint_as_float(rr[1]); }
;   l_reg = l_reg * alpha + ps;
;     ...
;   PK4(p0, 0, pa0); PK4(p0, 8, pa1); PK4(p1, 0, pa2); PK4(p1, 8, pa3);
;     ...
; }
; template <bool BANDED, bool FIXED> ...
;     ...
;     SBAR(); if (FIXED) qkt_c(pA0, pA1, K_lds, qr, r32, hi); else qkt(pA0, pA1, K_lds, qr, r32, hi, 0.f); MASK(pA0, pA1, j + 1);
;     finishSM(pB0, pB1, alB, l_reg, pa0, pa1, pa2, pa3); SBAR();
;     SLOAD(SE, min(j + 3, NT - 1)); SBAR();
;     pv_d0(o, vb0 + (int)SHM_V, pa0, pa1, pa2, pa3); partialSM<FIXED, !BANDED>(pA0, pA1, m_reg, mnA, alA);
;     __syncthreads(); SWAIT(); SWRITE(1, SO);
;     RESC(alA); __syncthreads();
	v_mfma_f32_32x32x16_bf16 v[80:95], v[164:167], v[128:131], v[80:95]
	s_min_u32 s40, s2, 0xfc
	s_add_i32 s100, s40, 3
	s_mul_i32 s100, s100, 0x60000
	v_add_u32_e32 v254, s100, v14
	v_add_u32_e32 v255, s100, v15
	global_load_dwordx4 v[160:163], v254, s[58:59]
	global_load_dwordx4 v[164:167], v255, s[58:59]
	global_load_dwordx4 v[168:171], v254, s[8:9]
	global_load_dwordx4 v[172:175], v255, s[8:9]
	v_exp_f32_e32 v188, v96
	v_add_f32_e32 v96, 0, v210
	v_add_f32_e32 v96, v211, v96
	v_add_f32_e32 v96, v212, v96
	v_add_f32_e32 v96, v213, v96
	v_add_f32_e32 v96, v214, v96
	v_add_f32_e32 v96, v215, v96
	v_add_f32_e32 v96, v216, v96
	v_add_f32_e32 v96, v217, v96
	v_add_f32_e32 v96, v218, v96
	v_add_f32_e32 v96, v219, v96
	v_add_f32_e32 v96, v220, v96
	v_add_f32_e32 v96, v221, v96
	v_add_f32_e32 v96, v222, v96
	v_exp_f32_e32 v189, v97
	v_add_f32_e32 v96, v223, v96
	v_exp_f32_e32 v190, v98
	v_add_f32_e32 v96, v224, v96
	v_exp_f32_e32 v191, v99
	v_add_f32_e32 v96, v225, v96
	v_exp_f32_e32 v192, v100
	v_add_f32_e32 v96, v188, v96
	v_exp_f32_e32 v193, v101
	v_add_f32_e32 v96, v189, v96
	v_exp_f32_e32 v194, v102
	v_add_f32_e32 v96, v190, v96
	v_exp_f32_e32 v195, v103
	v_add_f32_e32 v96, v191, v96
	v_add_f32_e32 v96, v192, v96
	v_add_f32_e32 v96, v193, v96
	v_add_f32_e32 v96, v194, v96
	v_add_f32_e32 v96, v195, v96
	v_add_f32_e32 v96, v104, v96
	v_add_f32_e32 v96, v105, v96
	v_add_f32_e32 v96, v106, v96
	v_add_f32_e32 v96, v107, v96
	v_add_f32_e32 v96, v108, v96
	v_add_f32_e32 v96, v109, v96
	v_add_f32_e32 v96, v110, v96
	v_add_f32_e32 v96, v111, v96
	v_mov_b32_e32 v97, v96
	s_nop 1
	v_permlane32_swap_b32_e32 v96, v97
	v_add_f32_e32 v96, v96, v97
	v_add_f32_e32 v183, v226, v96
	v_cvt_pk_bf16_f32 v96, v210, v211
	v_cvt_pk_bf16_f32 v97, v212, v213
	v_cvt_pk_bf16_f32 v98, v214, v215
	v_cvt_pk_bf16_f32 v99, v216, v217
	v_cvt_pk_bf16_f32 v100, v218, v219
	v_cvt_pk_bf16_f32 v101, v220, v221
	v_cvt_pk_bf16_f32 v102, v222, v223
	v_cvt_pk_bf16_f32 v103, v224, v225
	v_cvt_pk_bf16_f32 v111, v110, v111
	v_cvt_pk_bf16_f32 v110, v108, v109
	v_cvt_pk_bf16_f32 v109, v106, v107
	v_cvt_pk_bf16_f32 v108, v104, v105
	v_cvt_pk_bf16_f32 v104, v188, v189
	v_cvt_pk_bf16_f32 v105, v190, v191
	v_cvt_pk_bf16_f32 v106, v192, v193
	v_cvt_pk_bf16_f32 v107, v194, v195
	v_permlane32_swap_b32_e32 v96, v98
	v_permlane32_swap_b32_e32 v97, v99
	v_permlane32_swap_b32_e32 v100, v102
	v_permlane32_swap_b32_e32 v101, v103
	v_permlane32_swap_b32_e32 v104, v106
	v_permlane32_swap_b32_e32 v105, v107
	v_permlane32_swap_b32_e32 v109, v111
	v_permlane32_swap_b32_e32 v108, v110
	v_add_u32_e32 v255, vcc_hi, v208
	ds_read_b64_tr_b16 v[210:211], v255 offset:0
	ds_read_b64_tr_b16 v[212:213], v255 offset:0x800
	ds_read_b64_tr_b16 v[214:215], v255 offset:0x1000
	ds_read_b64_tr_b16 v[216:217], v255 offset:0x1800
	ds_read_b64_tr_b16 v[218:219], v255 offset:0x2000
	ds_read_b64_tr_b16 v[220:221], v255 offset:0x2800
	ds_read_b64_tr_b16 v[222:223], v255 offset:0x3000
	ds_read_b64_tr_b16 v[224:225], v255 offset:0x3800
	s_waitcnt lgkmcnt(0)
	s_nop 0
	v_mfma_f32_32x32x16_bf16 v[16:31], v[96:99], v[210:213], v[16:31]
	ds_read_b64_tr_b16 v[210:211], v255 offset:0x200
	ds_read_b64_tr_b16 v[212:213], v255 offset:0xa00
	v_mfma_f32_32x32x16_bf16 v[16:31], v[100:103], v[214:217], v[16:31]
	ds_read_b64_tr_b16 v[214:215], v255 offset:0x1200
	ds_read_b64_tr_b16 v[216:217], v255 offset:0x1a00
	v_mfma_f32_32x32x16_bf16 v[16:31], v[104:107], v[218:221], v[16:31]
	ds_read_b64_tr_b16 v[218:219], v255 offset:0x2200
	ds_read_b64_tr_b16 v[220:221], v255 offset:0x2a00
	v_mfma_f32_32x32x16_bf16 v[16:31], v[108:111], v[222:225], v[16:31]
	ds_read_b64_tr_b16 v[222:223], v255 offset:0x3200
	ds_read_b64_tr_b16 v[224:225], v255 offset:0x3a00
	s_waitcnt lgkmcnt(0)
	v_mfma_f32_32x32x16_bf16 v[32:47], v[96:99], v[210:213], v[32:47]
	ds_read_b64_tr_b16 v[210:211], v255 offset:0x400
	ds_read_b64_tr_b16 v[212:213], v255 offset:0xc00
	v_mfma_f32_32x32x16_bf16 v[32:47], v[100:103], v[214:217], v[32:47]
	ds_read_b64_tr_b16 v[214:215], v255 offset:0x1400
	ds_read_b64_tr_b16 v[216:217], v255 offset:0x1c00
	v_mfma_f32_32x32x16_bf16 v[32:47], v[104:107], v[218:221], v[32:47]
	ds_read_b64_tr_b16 v[218:219], v255 offset:0x2400
	ds_read_b64_tr_b16 v[220:221], v255 offset:0x2c00
	v_mfma_f32_32x32x16_bf16 v[32:47], v[108:111], v[222:225], v[32:47]
	ds_read_b64_tr_b16 v[222:223], v255 offset:0x3400
	ds_read_b64_tr_b16 v[224:225], v255 offset:0x3c00
	s_waitcnt lgkmcnt(0)
	v_mfma_f32_32x32x16_bf16 v[48:63], v[96:99], v[210:213], v[48:63]
	ds_read_b64_tr_b16 v[210:211], v255 offset:0x600
	ds_read_b64_tr_b16 v[212:213], v255 offset:0xe00
	v_mfma_f32_32x32x16_bf16 v[48:63], v[100:103], v[214:217], v[48:63]
	ds_read_b64_tr_b16 v[214:215], v255 offset:0x1600
	ds_read_b64_tr_b16 v[216:217], v255 offset:0x1e00
	v_mfma_f32_32x32x16_bf16 v[48:63], v[104:107], v[218:221], v[48:63]
	ds_read_b64_tr_b16 v[218:219], v255 offset:0x2600
	ds_read_b64_tr_b16 v[220:221], v255 offset:0x2e00
	v_mfma_f32_32x32x16_bf16 v[48:63], v[108:111], v[222:225], v[48:63]
	ds_read_b64_tr_b16 v[222:223], v255 offset:0x3600
	ds_read_b64_tr_b16 v[224:225], v255 offset:0x3e00
	s_waitcnt lgkmcnt(0)
	v_mfma_f32_32x32x16_bf16 v[64:79], v[96:99], v[210:213], v[64:79]
	v_exp_f32_e32 v210, v124
	v_exp_f32_e32 v213, v125
	v_exp_f32_e32 v211, v126
	v_exp_f32_e32 v212, v127
	v_mfma_f32_32x32x16_bf16 v[64:79], v[100:103], v[214:217], v[64:79]
	v_exp_f32_e32 v215, v120
	v_exp_f32_e32 v217, v121
	v_exp_f32_e32 v214, v122
	v_exp_f32_e32 v216, v123
	s_cmpk_gt_u32 s2, 0xfc
	v_mfma_f32_32x32x16_bf16 v[64:79], v[104:107], v[218:221], v[64:79]
	v_exp_f32_e32 v221, v114
	v_exp_f32_e32 v220, v116
	v_exp_f32_e32 v218, v118
	v_exp_f32_e32 v219, v119
	s_mov_b32 s100, vcc_lo
	s_mov_b32 vcc_lo, vcc_hi
	s_mov_b32 vcc_hi, s101
	s_mov_b32 s101, s100
	s_waitcnt lgkmcnt(0)
	s_barrier
; #define SBAR() __builtin_amdgcn_sched_barrier(0)
; #define RESC(a) do { if (!FIXED && __any((a) < 1.f)) { if (hi == 0) al_l[r32] = (a); asm volatile("s_waitcnt lgkmcnt(0)" ::: "memory"); \
;     _Pragma("unroll") for (int d = 0; d < 4; ++d) _Pragma("unroll") for (int r = 0; r < 16; ++r) o[d][r] *= al_l[crow(r, hi)]; } } while (0)
; #define MASK(P0, P1, t) do { if (BANDED) band_mask(P0, P1, rel00 + (t) * KVBLK, mlo, mhi); } while (0)
; __device__ __forceinline__ void finishSM(f32x16& p0, f32x16& p1, float alpha, float& l_reg, bf16x8& pa0, bf16x8& pa1, bf16x8& pa2, bf16x8& pa3) {
; #pragma unroll
;   for (int r = 0; r < 16; ++r) p1[r] = __builtin_amdgcn_exp2f(p1[r]);
;   float ps = 0;
; #pragma unroll
;   for (int r = 0; r < 16; ++r) ps += p0[r];
; #pragma unroll
;   for (int r = 0; r < 16; ++r) ps += p1[r];
;   { auto rr = __builtin_amdgcn_permlane32_swap(__float_as_uint(ps), __float_as_uint(ps), false, false);
;     ps = __uint_as_float(rr[0]) + __uint_as_float(rr[1]); }
;   l_reg = l_reg * alpha + ps;
;     ...
;   PK4(p0, 0, pa0); PK4(p0, 8, pa1); PK4(p1, 0, pa2); PK4(p1, 8, pa3);
;     ...
; }
; template <bool BANDED, bool FIXED> ...
;     ...
;   SBAR(); if (FIXED) qkt_c(pB0, pB1, (bf16*)((char*)K_lds + SHM_K), qr, r32, hi); else qkt(pB0, pB1, (bf16*)((char*)K_lds + SHM_K), qr, r32, hi, 0.f); MASK(pB0, pB1, NT - 1);
;   finishSM(pA0, pA1, alA, l_reg, pa0, pa1, pa2, pa3); SBAR();
;   pv_d0(o, vb0, pa0, pa1, pa2, pa3); partialSM<FIXED, !BANDED>(pB0, pB1, m_reg, mnB, alB);
;   __syncthreads(); RESC(alB);
;   finishSM(pB0, pB1, alB, l_reg, pa0, pa1, pa2, pa3); SBAR();
;   pv_d0(o, vb0 + (int)SHM_V, pa0, pa1, pa2, pa3);
	ds_read_b128 v[2:5], v200 offset:49152
	ds_read_b128 v[6:9], v200 offset:57344
	v_mfma_f32_32x32x16_bf16 v[64:79], v[108:111], v[222:225], v[64:79]
	v_exp_f32_e32 v223, v112
	v_exp_f32_e32 v225, v113
	v_exp_f32_e32 v224, v115
	v_exp_f32_e32 v222, v117
	s_cbranch_scc0 .LBB0_118
	v_mov_b32_e32 v188, 0x3c0881c4
	v_mov_b32_e32 v189, 0xbab64f3b
	v_mov_b32_e32 v190, 1
	v_bfrev_b32_e32 v191, 0.5
	v_mov_b32_e32 v192, 0xf149f2ca
	v_mov_b32_e32 v193, 0xff800000
	v_mov_b32_e32 v194, 0x41b17218
	v_not_b32_e32 v195, 63
	v_add_u32_e32 v255, vcc_hi, v208
	v_add_u32_e32 v254, s101, v208
	v_exp_f32_e32 v12, v80
	v_exp_f32_e32 v13, v81
	v_exp_f32_e32 v14, v82
	s_waitcnt lgkmcnt(1)
	v_mfma_f32_32x32x16_bf16 v[112:127], v[2:5], v[156:159], 0
	v_exp_f32_e32 v15, v83
	v_exp_f32_e32 v80, v84
	v_exp_f32_e32 v81, v85
	v_exp_f32_e32 v82, v86
	v_exp_f32_e32 v83, v87
	v_exp_f32_e32 v84, v88
	v_exp_f32_e32 v85, v89
	s_waitcnt lgkmcnt(0)
	v_mfma_f32_32x32x16_bf16 v[96:111], v[6:9], v[156:159], 0
	ds_read_b128 v[2:5], v201 offset:49152
	ds_read_b128 v[6:9], v201 offset:57344
	v_exp_f32_e32 v86, v90
	v_exp_f32_e32 v87, v91
	v_exp_f32_e32 v88, v92
	v_exp_f32_e32 v89, v93
	v_exp_f32_e32 v90, v94
	v_exp_f32_e32 v91, v95
	s_waitcnt lgkmcnt(1)
	v_mfma_f32_32x32x16_bf16 v[112:127], v[2:5], v[152:155], v[112:127]
	v_cvt_pk_bf16_f32 v10, v210, v213
	v_cvt_pk_bf16_f32 v11, v211, v212
	s_waitcnt lgkmcnt(0)
	v_mfma_f32_32x32x16_bf16 v[96:111], v[6:9], v[152:155], v[96:111]
	ds_read_b128 v[2:5], v202 offset:49152
	ds_read_b128 v[6:9], v202 offset:57344
	s_waitcnt lgkmcnt(1)
	v_mfma_f32_32x32x16_bf16 v[112:127], v[2:5], v[148:151], v[112:127]
	s_waitcnt lgkmcnt(0)
	v_mfma_f32_32x32x16_bf16 v[96:111], v[6:9], v[148:151], v[96:111]
	ds_read_b128 v[2:5], v203 offset:49152
	ds_read_b128 v[6:9], v203 offset:57344
	s_waitcnt lgkmcnt(1)
	v_mfma_f32_32x32x16_bf16 v[112:127], v[2:5], v[144:147], v[112:127]
	s_waitcnt lgkmcnt(0)
	v_mfma_f32_32x32x16_bf16 v[96:111], v[6:9], v[144:147], v[96:111]
	ds_read_b128 v[2:5], v206 offset:49152
	ds_read_b128 v[6:9], v206 offset:57344
	s_waitcnt lgkmcnt(1)
	v_mfma_f32_32x32x16_bf16 v[112:127], v[2:5], v[140:143], v[112:127]
	s_waitcnt lgkmcnt(0)
	v_mfma_f32_32x32x16_bf16 v[96:111], v[6:9], v[140:143], v[96:111]
	ds_read_b128 v[2:5], v204 offset:49152
	ds_read_b128 v[6:9], v204 offset:57344
	s_waitcnt lgkmcnt(1)
	v_mfma_f32_32x32x16_bf16 v[112:127], v[2:5], v[136:139], v[112:127]
	s_waitcnt lgkmcnt(0)
	v_mfma_f32_32x32x16_bf16 v[96:111], v[6:9], v[136:139], v[96:111]
	ds_read_b128 v[2:5], v205 offset:49152
	ds_read_b128 v[6:9], v205 offset:57344
	s_waitcnt lgkmcnt(1)
	v_mfma_f32_32x32x16_bf16 v[112:127], v[2:5], v[132:135], v[112:127]
	s_waitcnt lgkmcnt(0)
	v_mfma_f32_32x32x16_bf16 v[96:111], v[6:9], v[132:135], v[96:111]
	ds_read_b128 v[2:5], v207 offset:49152
	ds_read_b128 v[6:9], v207 offset:57344
	s_waitcnt lgkmcnt(1)
	v_mfma_f32_32x32x16_bf16 v[112:127], v[2:5], v[128:131], v[112:127]
	v_add_f32_e32 v2, 0, v223
	v_add_f32_e32 v2, v225, v2
	v_add_f32_e32 v2, v221, v2
	v_add_f32_e32 v2, v224, v2
	v_add_f32_e32 v2, v220, v2
	v_add_f32_e32 v2, v222, v2
	v_add_f32_e32 v2, v218, v2
	v_add_f32_e32 v2, v219, v2
	v_add_f32_e32 v2, v215, v2
	v_add_f32_e32 v2, v217, v2
	v_add_f32_e32 v2, v214, v2
	v_add_f32_e32 v2, v216, v2
	v_add_f32_e32 v2, v210, v2
	v_add_f32_e32 v2, v213, v2
	v_add_f32_e32 v2, v211, v2
	v_add_f32_e32 v2, v212, v2
	v_add_f32_e32 v2, v12, v2
	v_add_f32_e32 v2, v13, v2
	v_add_f32_e32 v2, v14, v2
	v_add_f32_e32 v2, v15, v2
	v_add_f32_e32 v2, v80, v2
	v_add_f32_e32 v2, v81, v2
	v_add_f32_e32 v2, v82, v2
	v_add_f32_e32 v2, v83, v2
	v_add_f32_e32 v2, v84, v2
	v_add_f32_e32 v2, v85, v2
	v_add_f32_e32 v2, v86, v2
	v_add_f32_e32 v2, v87, v2
	v_add_f32_e32 v2, v88, v2
	v_add_f32_e32 v2, v89, v2
	v_add_f32_e32 v2, v90, v2
	v_add_f32_e32 v2, v91, v2
	s_waitcnt lgkmcnt(0)
	v_mfma_f32_32x32x16_bf16 v[96:111], v[6:9], v[128:131], v[96:111]
	v_mov_b32_e32 v3, v2
	v_cvt_pk_bf16_f32 v4, v223, v225
	v_cvt_pk_bf16_f32 v5, v221, v224
	v_cvt_pk_bf16_f32 v6, v220, v222
	v_cvt_pk_bf16_f32 v7, v218, v219
	s_nop 1
	v_permlane32_swap_b32_e32 v2, v3
	v_permlane32_swap_b32_e32 v4, v6
	v_permlane32_swap_b32_e32 v5, v7
	v_cvt_pk_bf16_f32 v8, v215, v217
	v_cvt_pk_bf16_f32 v9, v214, v216
	v_cvt_pk_bf16_f32 v12, v12, v13
	v_cvt_pk_bf16_f32 v13, v14, v15
	v_cvt_pk_bf16_f32 v14, v80, v81
	v_cvt_pk_bf16_f32 v15, v82, v83
	v_cvt_pk_bf16_f32 v80, v84, v85
	v_cvt_pk_bf16_f32 v81, v86, v87
	v_cvt_pk_bf16_f32 v82, v88, v89
	v_cvt_pk_bf16_f32 v83, v90, v91
	s_nop 0
	v_permlane32_swap_b32_e32 v8, v10
	v_permlane32_swap_b32_e32 v9, v11
	v_permlane32_swap_b32_e32 v12, v14
	v_permlane32_swap_b32_e32 v13, v15
	v_permlane32_swap_b32_e32 v80, v82
	v_permlane32_swap_b32_e32 v81, v83
	ds_read_b64_tr_b16 v[84:85], v255 offset:0
	ds_read_b64_tr_b16 v[86:87], v255 offset:0x800
	ds_read_b64_tr_b16 v[88:89], v255 offset:0x1000
	ds_read_b64_tr_b16 v[90:91], v255 offset:0x1800
	ds_read_b64_tr_b16 v[92:93], v255 offset:0x2000
	ds_read_b64_tr_b16 v[94:95], v255 offset:0x2800
	ds_read_b64_tr_b16 v[128:129], v255 offset:0x3000
	ds_read_b64_tr_b16 v[130:131], v255 offset:0x3800
	s_waitcnt lgkmcnt(0)
	s_nop 0
	v_mfma_f32_32x32x16_bf16 v[16:31], v[4:7], v[84:87], v[16:31]
	ds_read_b64_tr_b16 v[84:85], v255 offset:0x200
	ds_read_b64_tr_b16 v[86:87], v255 offset:0xa00
	v_mfma_f32_32x32x16_bf16 v[16:31], v[8:11], v[88:91], v[16:31]
	ds_read_b64_tr_b16 v[88:89], v255 offset:0x1200
	ds_read_b64_tr_b16 v[90:91], v255 offset:0x1a00
	v_mfma_f32_32x32x16_bf16 v[16:31], v[12:15], v[92:95], v[16:31]
	ds_read_b64_tr_b16 v[92:93], v255 offset:0x2200
	ds_read_b64_tr_b16 v[94:95], v255 offset:0x2a00
	v_mfma_f32_32x32x16_bf16 v[16:31], v[80:83], v[128:131], v[16:31]
	ds_read_b64_tr_b16 v[128:129], v255 offset:0x3200
	ds_read_b64_tr_b16 v[130:131], v255 offset:0x3a00
	s_waitcnt lgkmcnt(0)
; #define SBAR() __builtin_amdgcn_sched_barrier(0)
; #define RESC(a) do { if (!FIXED && __any((a) < 1.f)) { if (hi == 0) al_l[r32] = (a); asm volatile("s_waitcnt lgkmcnt(0)" ::: "memory"); \
;     _Pragma("unroll") for (int d = 0; d < 4; ++d) _Pragma("unroll") for (int r = 0; r < 16; ++r) o[d][r] *= al_l[crow(r, hi)]; } } while (0)
; #define MASK(P0, P1, t) do { if (BANDED) band_mask(P0, P1, rel00 + (t) * KVBLK, mlo, mhi); } while (0)
; template <bool BANDED, bool FIXED> ...
;     ...
;   SBAR(); if (FIXED) qkt_c(pB0, pB1, (bf16*)((char*)K_lds + SHM_K), qr, r32, hi); else qkt(pB0, pB1, (bf16*)((char*)K_lds + SHM_K), qr, r32, hi, 0.f); MASK(pB0, pB1, NT - 1);
;   finishSM(pA0, pA1, alA, l_reg, pa0, pa1, pa2, pa3); SBAR();
;   pv_d0(o, vb0, pa0, pa1, pa2, pa3); partialSM<FIXED, !BANDED>(pB0, pB1, m_reg, mnB, alB);
;   __syncthreads(); RESC(alB);
;   finishSM(pB0, pB1, alB, l_reg, pa0, pa1, pa2, pa3); SBAR();
;   pv_d0(o, vb0 + (int)SHM_V, pa0, pa1, pa2, pa3);
;   if (!BANDED && wave >= 4) __builtin_amdgcn_s_setprio(0);
	v_mfma_f32_32x32x16_bf16 v[32:47], v[4:7], v[84:87], v[32:47]
	ds_read_b64_tr_b16 v[84:85], v255 offset:0x400
	ds_read_b64_tr_b16 v[86:87], v255 offset:0xc00
	v_mfma_f32_32x32x16_bf16 v[32:47], v[8:11], v[88:91], v[32:47]
	ds_read_b64_tr_b16 v[88:89], v255 offset:0x1400
	ds_read_b64_tr_b16 v[90:91], v255 offset:0x1c00
	v_mfma_f32_32x32x16_bf16 v[32:47], v[12:15], v[92:95], v[32:47]
	ds_read_b64_tr_b16 v[92:93], v255 offset:0x2400
	ds_read_b64_tr_b16 v[94:95], v255 offset:0x2c00
	v_mfma_f32_32x32x16_bf16 v[32:47], v[80:83], v[128:131], v[32:47]
	ds_read_b64_tr_b16 v[128:129], v255 offset:0x3400
	ds_read_b64_tr_b16 v[130:131], v255 offset:0x3c00
	s_waitcnt lgkmcnt(0)
	v_mfma_f32_32x32x16_bf16 v[48:63], v[4:7], v[84:87], v[48:63]
	ds_read_b64_tr_b16 v[84:85], v255 offset:0x600
	ds_read_b64_tr_b16 v[86:87], v255 offset:0xe00
	v_mfma_f32_32x32x16_bf16 v[48:63], v[8:11], v[88:91], v[48:63]
	ds_read_b64_tr_b16 v[88:89], v255 offset:0x1600
	ds_read_b64_tr_b16 v[90:91], v255 offset:0x1e00
	v_mfma_f32_32x32x16_bf16 v[48:63], v[12:15], v[92:95], v[48:63]
	ds_read_b64_tr_b16 v[92:93], v255 offset:0x2600
	ds_read_b64_tr_b16 v[94:95], v255 offset:0x2e00
	v_mfma_f32_32x32x16_bf16 v[48:63], v[80:83], v[128:131], v[48:63]
	ds_read_b64_tr_b16 v[128:129], v255 offset:0x3600
	ds_read_b64_tr_b16 v[130:131], v255 offset:0x3e00
	s_waitcnt lgkmcnt(0)
	v_mfma_f32_32x32x16_bf16 v[64:79], v[4:7], v[84:87], v[64:79]
	v_exp_f32_e32 v6, v112
	v_exp_f32_e32 v7, v113
	v_exp_f32_e32 v84, v126
	v_exp_f32_e32 v85, v127
	v_add_f32_e32 v4, 0, v6
	v_add_f32_e32 v4, v7, v4
	v_exp_f32_e32 v86, v96
	v_mfma_f32_32x32x16_bf16 v[64:79], v[8:11], v[88:91], v[64:79]
	v_exp_f32_e32 v8, v114
	v_exp_f32_e32 v9, v115
	v_exp_f32_e32 v10, v116
	v_exp_f32_e32 v11, v117
	v_add_f32_e32 v4, v8, v4
	v_add_f32_e32 v4, v9, v4
	v_add_f32_e32 v4, v10, v4
	v_mfma_f32_32x32x16_bf16 v[64:79], v[12:15], v[92:95], v[64:79]
	v_exp_f32_e32 v12, v118
	v_exp_f32_e32 v13, v119
	v_exp_f32_e32 v14, v120
	v_exp_f32_e32 v15, v121
	v_add_f32_e32 v4, v11, v4
	v_add_f32_e32 v4, v12, v4
	v_add_f32_e32 v4, v13, v4
	v_mfma_f32_32x32x16_bf16 v[64:79], v[80:83], v[128:131], v[64:79]
	v_exp_f32_e32 v80, v122
	v_exp_f32_e32 v81, v123
	v_exp_f32_e32 v82, v124
	v_add_f32_e32 v4, v14, v4
	v_exp_f32_e32 v83, v125
	v_add_f32_e32 v4, v15, v4
	v_add_f32_e32 v4, v80, v4
	v_add_f32_e32 v4, v81, v4
	v_add_f32_e32 v4, v82, v4
	v_exp_f32_e32 v87, v97
	v_add_f32_e32 v4, v83, v4
	v_exp_f32_e32 v88, v98
	v_add_f32_e32 v4, v84, v4
	v_exp_f32_e32 v89, v99
	v_add_f32_e32 v4, v85, v4
	v_exp_f32_e32 v90, v100
	v_add_f32_e32 v4, v86, v4
	v_exp_f32_e32 v91, v101
	v_add_f32_e32 v4, v87, v4
	v_exp_f32_e32 v92, v102
	v_add_f32_e32 v4, v88, v4
	v_exp_f32_e32 v93, v103
	v_add_f32_e32 v4, v89, v4
	v_exp_f32_e32 v94, v104
	v_add_f32_e32 v4, v90, v4
	v_exp_f32_e32 v95, v105
	v_add_f32_e32 v4, v91, v4
	v_exp_f32_e32 v96, v106
	v_add_f32_e32 v4, v92, v4
	v_exp_f32_e32 v97, v107
	v_add_f32_e32 v4, v93, v4
	v_exp_f32_e32 v98, v108
	v_add_f32_e32 v4, v94, v4
	v_exp_f32_e32 v99, v109
	v_add_f32_e32 v4, v95, v4
	v_exp_f32_e32 v100, v110
	v_add_f32_e32 v4, v96, v4
	v_exp_f32_e32 v101, v111
	v_add_f32_e32 v4, v97, v4
	v_add_f32_e32 v4, v98, v4
	v_add_f32_e32 v4, v99, v4
	v_add_f32_e32 v4, v100, v4
	v_add_f32_e32 v4, v101, v4
	v_mov_b32_e32 v5, v4
	s_nop 1
	v_permlane32_swap_b32_e32 v4, v5
	v_cvt_pk_bf16_f32 v6, v6, v7
	v_cvt_pk_bf16_f32 v7, v8, v9
	v_cvt_pk_bf16_f32 v8, v10, v11
	v_cvt_pk_bf16_f32 v9, v12, v13
	v_cvt_pk_bf16_f32 v10, v14, v15
	v_cvt_pk_bf16_f32 v11, v80, v81
	v_cvt_pk_bf16_f32 v12, v82, v83
	v_cvt_pk_bf16_f32 v13, v84, v85
	v_cvt_pk_bf16_f32 v80, v86, v87
	v_cvt_pk_bf16_f32 v81, v88, v89
	v_cvt_pk_bf16_f32 v82, v90, v91
	v_cvt_pk_bf16_f32 v83, v92, v93
	v_cvt_pk_bf16_f32 v84, v94, v95
	v_cvt_pk_bf16_f32 v85, v96, v97
	v_cvt_pk_bf16_f32 v86, v98, v99
	v_cvt_pk_bf16_f32 v87, v100, v101
	s_barrier
	v_permlane32_swap_b32_e32 v6, v8
	v_permlane32_swap_b32_e32 v7, v9
	v_permlane32_swap_b32_e32 v10, v12
	v_permlane32_swap_b32_e32 v11, v13
	v_permlane32_swap_b32_e32 v80, v82
	v_permlane32_swap_b32_e32 v81, v83
	v_permlane32_swap_b32_e32 v84, v86
	v_permlane32_swap_b32_e32 v85, v87
	ds_read_b64_tr_b16 v[88:89], v254 offset:0
	ds_read_b64_tr_b16 v[90:91], v254 offset:0x800
	ds_read_b64_tr_b16 v[92:93], v254 offset:0x1000
	ds_read_b64_tr_b16 v[94:95], v254 offset:0x1800
	ds_read_b64_tr_b16 v[96:97], v254 offset:0x2000
	ds_read_b64_tr_b16 v[98:99], v254 offset:0x2800
	ds_read_b64_tr_b16 v[100:101], v254 offset:0x3000
	ds_read_b64_tr_b16 v[102:103], v254 offset:0x3800
	s_waitcnt lgkmcnt(0)
	s_nop 0
	v_mfma_f32_32x32x16_bf16 v[16:31], v[6:9], v[88:91], v[16:31]
	ds_read_b64_tr_b16 v[88:89], v254 offset:0x200
	ds_read_b64_tr_b16 v[90:91], v254 offset:0xa00
	v_mfma_f32_32x32x16_bf16 v[16:31], v[10:13], v[92:95], v[16:31]
	ds_read_b64_tr_b16 v[92:93], v254 offset:0x1200
	ds_read_b64_tr_b16 v[94:95], v254 offset:0x1a00
	v_mfma_f32_32x32x16_bf16 v[16:31], v[80:83], v[96:99], v[16:31]
	ds_read_b64_tr_b16 v[96:97], v254 offset:0x2200
	ds_read_b64_tr_b16 v[98:99], v254 offset:0x2a00
	v_mfma_f32_32x32x16_bf16 v[16:31], v[84:87], v[100:103], v[16:31]
	ds_read_b64_tr_b16 v[100:101], v254 offset:0x3200
	ds_read_b64_tr_b16 v[102:103], v254 offset:0x3a00
	s_waitcnt lgkmcnt(0)
	v_mfma_f32_32x32x16_bf16 v[32:47], v[6:9], v[88:91], v[32:47]
	ds_read_b64_tr_b16 v[88:89], v254 offset:0x400
	ds_read_b64_tr_b16 v[90:91], v254 offset:0xc00
	v_mfma_f32_32x32x16_bf16 v[32:47], v[10:13], v[92:95], v[32:47]
	ds_read_b64_tr_b16 v[92:93], v254 offset:0x1400
	ds_read_b64_tr_b16 v[94:95], v254 offset:0x1c00
	v_mfma_f32_32x32x16_bf16 v[32:47], v[80:83], v[96:99], v[32:47]
	ds_read_b64_tr_b16 v[96:97], v254 offset:0x2400
	ds_read_b64_tr_b16 v[98:99], v254 offset:0x2c00
	v_mfma_f32_32x32x16_bf16 v[32:47], v[84:87], v[100:103], v[32:47]
	ds_read_b64_tr_b16 v[100:101], v254 offset:0x3400
	ds_read_b64_tr_b16 v[102:103], v254 offset:0x3c00
	s_waitcnt lgkmcnt(0)
	v_mfma_f32_32x32x16_bf16 v[48:63], v[6:9], v[88:91], v[48:63]
	ds_read_b64_tr_b16 v[88:89], v254 offset:0x600
	ds_read_b64_tr_b16 v[90:91], v254 offset:0xe00
	v_mfma_f32_32x32x16_bf16 v[48:63], v[10:13], v[92:95], v[48:63]
	ds_read_b64_tr_b16 v[92:93], v254 offset:0x1600
	ds_read_b64_tr_b16 v[94:95], v254 offset:0x1e00
	v_mfma_f32_32x32x16_bf16 v[48:63], v[80:83], v[96:99], v[48:63]
	ds_read_b64_tr_b16 v[96:97], v254 offset:0x2600
	ds_read_b64_tr_b16 v[98:99], v254 offset:0x2e00
	v_mfma_f32_32x32x16_bf16 v[48:63], v[84:87], v[100:103], v[48:63]
	ds_read_b64_tr_b16 v[100:101], v254 offset:0x3600
	ds_read_b64_tr_b16 v[102:103], v254 offset:0x3e00
	s_waitcnt lgkmcnt(0)
	v_mfma_f32_32x32x16_bf16 v[64:79], v[6:9], v[88:91], v[64:79]
	s_and_b64 vcc, exec, s[22:23]
	v_mfma_f32_32x32x16_bf16 v[64:79], v[10:13], v[92:95], v[64:79]
	v_mfma_f32_32x32x16_bf16 v[64:79], v[80:83], v[96:99], v[64:79]
	v_mfma_f32_32x32x16_bf16 v[64:79], v[84:87], v[100:103], v[64:79]
	s_cbranch_vccz .LBB0_121
	s_setprio 0
